# grid barrier generation polls keep 4 loads in flight (XGEN waiters and TOPGEN leaders sample ~4x as often)
# speedup vs baseline: 1.0010x; 1.0010x over previous
; __device__ __forceinline__ unsigned xb_ld(unsigned* p)              { return __hip_atomic_load(p, __ATOMIC_RELAXED, __HIP_MEMORY_SCOPE_AGENT); }
; __device__ __forceinline__ unsigned xb_add(unsigned* p, unsigned v) { return __hip_atomic_fetch_add(p, v, __ATOMIC_RELAXED, __HIP_MEMORY_SCOPE_AGENT); }
; #define XB_SPIN(cond, bar) do { unsigned _sp = 0; while (cond) { __builtin_amdgcn_s_sleep(1); \
;     if ((++_sp & 255u) == 0u) { if (xb_ld(&(bar)[XB_TMO])) break; if (_sp > XB_SPIN_CAP) { atomicAdd(&(bar)[XB_TMO], 1u); break; } } } } while (0)
; __device__ __forceinline__ void xcd_barrier(const XcdBarrier& b) {
;     ...
;         const unsigned old = xb_add(&bar[XB_XSUB(b.x)], 1u);
;         const unsigned gen = old / nloc;
;         if (old + 1u == (gen + 1u) * nloc) {
;             __builtin_amdgcn_fence(__ATOMIC_RELEASE, "agent");
;             asm volatile("s_waitcnt vmcnt(0)" ::: "memory");
;             const unsigned og = xb_add(&bar[XB_TOP], 1u);
;             const unsigned tg = og / nx;
;             if (og + 1u == (tg + 1u) * nx) xb_add(&bar[XB_TOPGEN], 1u);
;             else XB_SPIN(xb_ld(&bar[XB_TOPGEN]) == tg, bar);
;             __builtin_amdgcn_fence(__ATOMIC_ACQUIRE, "agent");
;             xb_add(&bar[XB_XGEN(b.x)], 1u);
;             asm volatile("s_waitcnt vmcnt(0)" ::: "memory");
;         } else {
;             XB_SPIN(xb_ld(&bar[XB_XGEN(b.x)]) == gen, bar);
.Lbar_early_done:
	s_waitcnt lgkmcnt(0)
	global_load_dword v2, v227, s[8:9] offset:1024 sc1
	s_add_u32 s22, s8, 0x2400
	s_addc_u32 s23, s9, 0
	s_waitcnt vmcnt(0)
	v_cmp_eq_u32_e32 vcc, v2, v0
	s_and_saveexec_b64 s[18:19], vcc
	s_cbranch_execz .LBB0_813
	s_add_u32 s20, s2, 0x13a40200
	s_addc_u32 s21, s3, 0
	s_mov_b32 s38, 1
	s_mov_b64 s[24:25], 0
	v_mov_b32_e32 v6, v0
	s_branch .LBB0_804

; __device__ __forceinline__ unsigned xb_ld(unsigned* p)              { return __hip_atomic_load(p, __ATOMIC_RELAXED, __HIP_MEMORY_SCOPE_AGENT); }
; #define XB_SPIN(cond, bar) do { unsigned _sp = 0; while (cond) { __builtin_amdgcn_s_sleep(1); \
;     if ((++_sp & 255u) == 0u) { if (xb_ld(&(bar)[XB_TMO])) break; if (_sp > XB_SPIN_CAP) { atomicAdd(&(bar)[XB_TMO], 1u); break; } } } } while (0)
; __device__ __forceinline__ void xcd_barrier(const XcdBarrier& b) {
;     ...
;             XB_SPIN(xb_ld(&bar[XB_XGEN(b.x)]) == gen, bar);
.LBB0_808:
	global_load_dword v6, v1, s[22:23] sc1
	s_add_i32 s38, s38, 1
	s_mov_b64 s[34:35], -1
	s_waitcnt vmcnt(3)
	v_cmp_ne_u32_e32 vcc, v6, v0
	s_orn2_b64 s[30:31], vcc, exec
	s_branch .LBB0_803

; __device__ __forceinline__ unsigned xb_ld(unsigned* p)              { return __hip_atomic_load(p, __ATOMIC_RELAXED, __HIP_MEMORY_SCOPE_AGENT); }
; __device__ __forceinline__ unsigned xb_add(unsigned* p, unsigned v) { return __hip_atomic_fetch_add(p, v, __ATOMIC_RELAXED, __HIP_MEMORY_SCOPE_AGENT); }
; #define XB_SPIN(cond, bar) do { unsigned _sp = 0; while (cond) { __builtin_amdgcn_s_sleep(1); \
;     if ((++_sp & 255u) == 0u) { if (xb_ld(&(bar)[XB_TMO])) break; if (_sp > XB_SPIN_CAP) { atomicAdd(&(bar)[XB_TMO], 1u); break; } } } } while (0)
; __device__ __forceinline__ void xcd_barrier(const XcdBarrier& b) {
;     ...
;         if (old + 1u == (gen + 1u) * nloc) {
;             __builtin_amdgcn_fence(__ATOMIC_RELEASE, "agent");
;             asm volatile("s_waitcnt vmcnt(0)" ::: "memory");
;             const unsigned og = xb_add(&bar[XB_TOP], 1u);
;             const unsigned tg = og / nx;
;             if (og + 1u == (tg + 1u) * nx) xb_add(&bar[XB_TOPGEN], 1u);
;             else XB_SPIN(xb_ld(&bar[XB_TOPGEN]) == tg, bar);
.LBB0_817:
	s_or_b64 exec, exec, s[18:19]
	s_waitcnt vmcnt(0)
	v_readfirstlane_b32 s10, v3
	v_sub_u32_e32 v4, 0, v2
	s_mov_b64 s[20:21], -1
	v_add_u32_e32 v3, s10, v0
	v_cvt_f32_u32_e32 v0, v2
	s_add_u32 s10, s2, 0x13a43500
	s_addc_u32 s11, s3, 0
	v_rcp_iflag_f32_e32 v0, v0
	s_nop 0
	v_mul_f32_e32 v0, 0x4f7ffffe, v0
	v_cvt_u32_f32_e32 v0, v0
	v_mul_lo_u32 v4, v4, v0
	v_mul_hi_u32 v4, v0, v4
	v_add_u32_e32 v0, v0, v4
	v_mul_hi_u32 v0, v3, v0
	v_mul_lo_u32 v4, v0, v2
	v_sub_u32_e32 v4, v3, v4
	v_cmp_ge_u32_e32 vcc, v4, v2
	v_add_u32_e32 v5, 1, v0
	v_add_u32_e32 v3, 1, v3
	v_cndmask_b32_e32 v0, v0, v5, vcc
	v_sub_u32_e32 v5, v4, v2
	v_cndmask_b32_e32 v4, v4, v5, vcc
	v_cmp_ge_u32_e32 vcc, v4, v2
	v_add_u32_e32 v4, 1, v0
	s_nop 0
	v_cndmask_b32_e32 v0, v0, v4, vcc
	v_mul_lo_u32 v4, v2, v0
	v_add_u32_e32 v2, v4, v2
	v_cmp_ne_u32_e32 vcc, v3, v2
	v_mov_b64_e32 v[2:3], s[10:11]
	s_and_saveexec_b64 s[18:19], vcc
	s_cbranch_execz .LBB0_829
	global_load_dword v2, v1, s[10:11] sc1
	s_mov_b64 s[24:25], 0
	s_waitcnt vmcnt(0)
	v_cmp_eq_u32_e32 vcc, v2, v0
	s_and_saveexec_b64 s[22:23], vcc
	s_cbranch_execz .LBB0_828
	s_add_u32 s20, s2, 0x13a40200
	s_addc_u32 s21, s3, 0
	s_mov_b32 s38, 1
	v_mov_b32_e32 v6, v0
	s_branch .LBB0_821

; __device__ __forceinline__ unsigned xb_ld(unsigned* p)              { return __hip_atomic_load(p, __ATOMIC_RELAXED, __HIP_MEMORY_SCOPE_AGENT); }
; #define XB_SPIN(cond, bar) do { unsigned _sp = 0; while (cond) { __builtin_amdgcn_s_sleep(1); \
;     if ((++_sp & 255u) == 0u) { if (xb_ld(&(bar)[XB_TMO])) break; if (_sp > XB_SPIN_CAP) { atomicAdd(&(bar)[XB_TMO], 1u); break; } } } } while (0)
; __device__ __forceinline__ void xcd_barrier(const XcdBarrier& b) {
;     ...
;             else XB_SPIN(xb_ld(&bar[XB_TOPGEN]) == tg, bar);
.LBB0_825:
	global_load_dword v6, v1, s[10:11] sc1
	s_add_i32 s38, s38, 1
	s_mov_b64 s[34:35], -1
	s_waitcnt vmcnt(3)
	v_cmp_ne_u32_e32 vcc, v6, v0
	s_orn2_b64 s[30:31], vcc, exec
	s_branch .LBB0_820
